# opt48: opt46 stack (full-sector G2 epilogue, early K reads, nt bf16 stores) + flat priority in both attention phases
# baseline (speedup 1.0000x reference)
; #define CLASSIFY(kv0_, act_, cls_) do { act_ = true; if (SWA) act_ = ((kv0_) + 63 >= qw - 128) && ((kv0_) <= qw + 159); \
;         cls_ = 0; if ((kv0_) + 63 < qw) cls_ = 1; else if ((kv0_) > qw + 31) cls_ = 2; \
;         if (SWA) { if (cls_ == 1 && qw + 31 - (kv0_) > 128) cls_ = 0; if (cls_ == 2 && (kv0_) + 63 - qw > 128) cls_ = 0; } } while (0)
; template <bool SWA>
; __device__ __forceinline__ void unit(LAS unsigned char* lds, const bf16_t* PROJ, const bf16_t* KT, const bf16_t* VT, bf16_t* OB, int opitch, int ocol, int b, int head, int qb, float slope2, float m_init, float lam, const float* subg) {
;     ...
;         const int kva = TILE_OF(sa) * 64, kvb = TILE_OF(sb < nsteps ? sb : sa) * 64;
;         bool acta, actb; int clsa, clsb;
;         CLASSIFY(kva, acta, clsa); CLASSIFY(kvb, actb, clsb); actb = actb && (sb < nsteps);
.LBB0_887:
	s_add_i32 s28, s1, -4
	s_and_b64 s[6:7], s[78:79], exec
	s_cselect_b32 s6, s27, s28
	s_lshl_b32 s28, s6, 6
	s_or_b32 s6, s28, 63
	s_cmp_ge_i32 s6, s5
	s_cselect_b64 s[86:87], -1, 0
	s_cmp_lt_i32 s6, s5
	s_cselect_b64 s[78:79], -1, 0
	s_cmp_le_i32 s28, s19
	s_cselect_b64 s[88:89], -1, 0
	s_add_i32 s6, s25, 0xffff4000
	s_and_b32 s6, s6, 0x8000
	s_add_i32 s29, s6, 0
	s_and_b64 s[80:81], s[86:87], s[88:89]

	s_waitcnt lgkmcnt(0)
	v_mfma_f32_32x32x16_bf16 v[112:127], v[66:69], v[140:143], v[96:111]
	s_waitcnt lgkmcnt(6)
	v_mfma_f32_32x32x16_bf16 v[96:111], v[70:73], v[140:143], v[96:111]
	s_waitcnt lgkmcnt(5)
	v_mfma_f32_32x32x16_bf16 v[112:127], v[74:77], v[136:139], v[112:127]
	s_waitcnt lgkmcnt(4)
	v_mfma_f32_32x32x16_bf16 v[96:111], v[78:81], v[136:139], v[96:111]
	s_waitcnt lgkmcnt(3)
	v_mfma_f32_32x32x16_bf16 v[112:127], v[82:85], v[132:135], v[112:127]
	s_waitcnt lgkmcnt(2)
	v_mfma_f32_32x32x16_bf16 v[96:111], v[86:89], v[132:135], v[96:111]
	s_waitcnt lgkmcnt(1)
	v_mfma_f32_32x32x16_bf16 v[112:127], v[90:93], v[128:131], v[112:127]
	s_waitcnt lgkmcnt(0)
	v_mfma_f32_32x32x16_bf16 v[96:111], v[204:207], v[128:131], v[96:111]

	s_mov_b32 m0, s32
	s_nop 0
	global_load_lds_dwordx4 v164, s[98:99]
	s_add_i32 m0, s32, 0x400
	s_nop 0
	global_load_lds_dwordx4 v170, s[98:99]
	s_and_b64 vcc, exec, s[80:81]
	v_mov_b32_e32 v65, 0
	v_mov_b32_e32 v66, 0
	v_mov_b32_e32 v67, 0
	v_mov_b32_e32 v68, 0
	v_mov_b32_e32 v69, 0
	v_mov_b32_e32 v70, 0
	v_mov_b32_e32 v71, 0
	v_mov_b32_e32 v72, 0
	v_mov_b32_e32 v73, 0
	v_mov_b32_e32 v74, 0
	v_mov_b32_e32 v75, 0
	v_mov_b32_e32 v76, 0
	v_mov_b32_e32 v77, 0
	v_mov_b32_e32 v78, 0
	v_mov_b32_e32 v79, 0
	s_cbranch_vccnz .LBB0_889
	s_and_b64 s[6:7], s[88:89], exec
	s_cselect_b32 s27, 0, 64
	s_and_b64 s[6:7], s[86:87], exec
	s_cselect_b32 s6, s27, 0
	s_add_i32 s6, s6, 0
	s_add_i32 s6, s6, 0x20200
	v_mov_b32_e32 v76, s6
	ds_read_b128 v[64:67], v76
	ds_read_b128 v[68:71], v76 offset:16
	ds_read_b128 v[72:75], v76 offset:32
	ds_read_b128 v[76:79], v76 offset:48
